# plus hand-scheduled gated O-GEMM epilogue (all gate loads in flight, T ring)
# speedup vs baseline: 1.0214x; 1.0052x over previous
.LBB2_257:
	s_cmp_eq_u32 s11, 0
	s_mov_b32 s8, 0x7800000
	v_lshl_add_u32 v142, s15, 8, v164
	v_lshl_or_b32 v140, s14, 8, v166
	s_cselect_b32 s8, s8, 0x9800000
	v_ashrrev_i32_e32 v143, 31, v142
	v_readlane_b32 s14, v254, 48
	v_ashrrev_i32_e32 v141, 31, v140
	v_lshlrev_b64 v[144:145], 11, v[142:143]
	v_readlane_b32 s15, v254, 49
	s_nop 1
	s_add_u32 s50, s14, s8
	v_lshl_add_u64 v[144:145], v[144:145], 0, v[140:141]
	s_addc_u32 s51, s15, 0
	v_readlane_b32 s20, v254, 38
	v_readlane_b32 s22, v254, 36
	v_readlane_b32 s21, v254, 39
	v_readlane_b32 s23, v254, 37
	s_mov_b64 s[100:101], 0x10000
	s_mov_b64 s[38:39], 0x20000
	v_lshl_add_u64 v[160:161], v[144:145], 1, s[50:51]
	v_lshl_add_u64 v[162:163], v[144:145], 2, s[6:7]
	v_lshl_add_u64 v[142:143], v[144:145], 1, s[12:13]
	global_load_dwordx4 v[168:171], v[160:161], off
	global_load_dwordx4 v[172:175], v[160:161], off offset:256
	v_lshl_add_u64 v[160:161], v[160:161], 0, s[100:101]
	global_load_dwordx4 v[176:179], v[160:161], off
	global_load_dwordx4 v[180:183], v[160:161], off offset:256
	v_lshl_add_u64 v[160:161], v[160:161], 0, s[100:101]
	global_load_dwordx4 v[184:187], v[160:161], off
	global_load_dwordx4 v[192:195], v[160:161], off offset:256
	v_lshl_add_u64 v[160:161], v[160:161], 0, s[100:101]
	global_load_dwordx4 v[196:199], v[160:161], off
	global_load_dwordx4 v[200:203], v[160:161], off offset:256
	v_lshl_add_u64 v[160:161], s[100:101], 2, v[160:161]
	v_lshl_add_u64 v[160:161], v[160:161], 0, s[100:101]
	global_load_dwordx4 v[204:207], v[160:161], off
	global_load_dwordx4 v[208:211], v[160:161], off offset:256
	v_lshl_add_u64 v[160:161], v[160:161], 0, s[100:101]
	global_load_dwordx4 v[212:215], v[160:161], off
	global_load_dwordx4 v[216:219], v[160:161], off offset:256
	v_lshl_add_u64 v[160:161], v[160:161], 0, s[100:101]
	global_load_dwordx4 v[220:223], v[160:161], off
	global_load_dwordx4 v[224:227], v[160:161], off offset:256
	v_lshl_add_u64 v[160:161], v[160:161], 0, s[100:101]
	global_load_dwordx4 v[228:231], v[160:161], off
	global_load_dwordx4 v[232:235], v[160:161], off offset:256
	s_cmp_lg_u32 s11, 0
	s_cbranch_scc1 .Lepiof_z1
	s_waitcnt vmcnt(15)
	v_cvt_f32_f16_e32 v236, v168
	v_cvt_f32_f16_sdwa v237, v168 dst_sel:DWORD dst_unused:UNUSED_PAD src0_sel:WORD_1
	v_cvt_f32_f16_e32 v238, v169
	v_cvt_f32_f16_sdwa v239, v169 dst_sel:DWORD dst_unused:UNUSED_PAD src0_sel:WORD_1
	v_cvt_f32_f16_e32 v240, v170
	v_cvt_f32_f16_sdwa v241, v170 dst_sel:DWORD dst_unused:UNUSED_PAD src0_sel:WORD_1
	v_cvt_f32_f16_e32 v242, v171
	v_cvt_f32_f16_sdwa v243, v171 dst_sel:DWORD dst_unused:UNUSED_PAD src0_sel:WORD_1
	v_pk_mul_f32 v[126:127], v[126:127], v[236:237]
	v_pk_mul_f32 v[128:129], v[128:129], v[238:239]
	v_pk_mul_f32 v[122:123], v[122:123], v[240:241]
	v_pk_mul_f32 v[124:125], v[124:125], v[242:243]
	global_store_dwordx4 v[162:163], v[126:129], off
	global_store_dwordx4 v[162:163], v[122:125], off offset:16
	s_waitcnt vmcnt(16)
	v_cvt_f32_f16_e32 v236, v172
	v_cvt_f32_f16_sdwa v237, v172 dst_sel:DWORD dst_unused:UNUSED_PAD src0_sel:WORD_1
	v_cvt_f32_f16_e32 v238, v173
	v_cvt_f32_f16_sdwa v239, v173 dst_sel:DWORD dst_unused:UNUSED_PAD src0_sel:WORD_1
	v_cvt_f32_f16_e32 v240, v174
	v_cvt_f32_f16_sdwa v241, v174 dst_sel:DWORD dst_unused:UNUSED_PAD src0_sel:WORD_1
	v_cvt_f32_f16_e32 v242, v175
	v_cvt_f32_f16_sdwa v243, v175 dst_sel:DWORD dst_unused:UNUSED_PAD src0_sel:WORD_1
	v_pk_mul_f32 v[118:119], v[118:119], v[236:237]
	v_pk_mul_f32 v[120:121], v[120:121], v[238:239]
	v_pk_mul_f32 v[114:115], v[114:115], v[240:241]
	v_pk_mul_f32 v[116:117], v[116:117], v[242:243]
	global_store_dwordx4 v[162:163], v[118:121], off offset:512
	global_store_dwordx4 v[162:163], v[114:117], off offset:528
	v_lshl_add_u64 v[162:163], v[162:163], 0, s[38:39]
	s_waitcnt vmcnt(17)
	v_cvt_f32_f16_e32 v236, v176
	v_cvt_f32_f16_sdwa v237, v176 dst_sel:DWORD dst_unused:UNUSED_PAD src0_sel:WORD_1
	v_cvt_f32_f16_e32 v238, v177
	v_cvt_f32_f16_sdwa v239, v177 dst_sel:DWORD dst_unused:UNUSED_PAD src0_sel:WORD_1
	v_cvt_f32_f16_e32 v240, v178
	v_cvt_f32_f16_sdwa v241, v178 dst_sel:DWORD dst_unused:UNUSED_PAD src0_sel:WORD_1
	v_cvt_f32_f16_e32 v242, v179
	v_cvt_f32_f16_sdwa v243, v179 dst_sel:DWORD dst_unused:UNUSED_PAD src0_sel:WORD_1
	v_pk_mul_f32 v[110:111], v[110:111], v[236:237]
	v_pk_mul_f32 v[112:113], v[112:113], v[238:239]
	v_pk_mul_f32 v[106:107], v[106:107], v[240:241]
	v_pk_mul_f32 v[108:109], v[108:109], v[242:243]
	global_store_dwordx4 v[162:163], v[110:113], off
	global_store_dwordx4 v[162:163], v[106:109], off offset:16
	s_waitcnt vmcnt(18)
	v_cvt_f32_f16_e32 v236, v180
	v_cvt_f32_f16_sdwa v237, v180 dst_sel:DWORD dst_unused:UNUSED_PAD src0_sel:WORD_1
	v_cvt_f32_f16_e32 v238, v181
	v_cvt_f32_f16_sdwa v239, v181 dst_sel:DWORD dst_unused:UNUSED_PAD src0_sel:WORD_1
	v_cvt_f32_f16_e32 v240, v182
	v_cvt_f32_f16_sdwa v241, v182 dst_sel:DWORD dst_unused:UNUSED_PAD src0_sel:WORD_1
	v_cvt_f32_f16_e32 v242, v183
	v_cvt_f32_f16_sdwa v243, v183 dst_sel:DWORD dst_unused:UNUSED_PAD src0_sel:WORD_1
	v_pk_mul_f32 v[102:103], v[102:103], v[236:237]
	v_pk_mul_f32 v[104:105], v[104:105], v[238:239]
	v_pk_mul_f32 v[98:99], v[98:99], v[240:241]
	v_pk_mul_f32 v[100:101], v[100:101], v[242:243]
	global_store_dwordx4 v[162:163], v[102:105], off offset:512
	global_store_dwordx4 v[162:163], v[98:101], off offset:528
	v_lshl_add_u64 v[162:163], v[162:163], 0, s[38:39]
	s_waitcnt vmcnt(19)
	v_cvt_f32_f16_e32 v236, v184
	v_cvt_f32_f16_sdwa v237, v184 dst_sel:DWORD dst_unused:UNUSED_PAD src0_sel:WORD_1
	v_cvt_f32_f16_e32 v238, v185
	v_cvt_f32_f16_sdwa v239, v185 dst_sel:DWORD dst_unused:UNUSED_PAD src0_sel:WORD_1
	v_cvt_f32_f16_e32 v240, v186
	v_cvt_f32_f16_sdwa v241, v186 dst_sel:DWORD dst_unused:UNUSED_PAD src0_sel:WORD_1
	v_cvt_f32_f16_e32 v242, v187
	v_cvt_f32_f16_sdwa v243, v187 dst_sel:DWORD dst_unused:UNUSED_PAD src0_sel:WORD_1
	v_pk_mul_f32 v[94:95], v[94:95], v[236:237]
	v_pk_mul_f32 v[96:97], v[96:97], v[238:239]
	v_pk_mul_f32 v[90:91], v[90:91], v[240:241]
	v_pk_mul_f32 v[92:93], v[92:93], v[242:243]
	global_store_dwordx4 v[162:163], v[94:97], off
	global_store_dwordx4 v[162:163], v[90:93], off offset:16
	s_waitcnt vmcnt(20)
	v_cvt_f32_f16_e32 v236, v192
	v_cvt_f32_f16_sdwa v237, v192 dst_sel:DWORD dst_unused:UNUSED_PAD src0_sel:WORD_1
	v_cvt_f32_f16_e32 v238, v193
	v_cvt_f32_f16_sdwa v239, v193 dst_sel:DWORD dst_unused:UNUSED_PAD src0_sel:WORD_1
	v_cvt_f32_f16_e32 v240, v194
	v_cvt_f32_f16_sdwa v241, v194 dst_sel:DWORD dst_unused:UNUSED_PAD src0_sel:WORD_1
	v_cvt_f32_f16_e32 v242, v195
	v_cvt_f32_f16_sdwa v243, v195 dst_sel:DWORD dst_unused:UNUSED_PAD src0_sel:WORD_1
	v_pk_mul_f32 v[86:87], v[86:87], v[236:237]
	v_pk_mul_f32 v[88:89], v[88:89], v[238:239]
	v_pk_mul_f32 v[82:83], v[82:83], v[240:241]
	v_pk_mul_f32 v[84:85], v[84:85], v[242:243]
	global_store_dwordx4 v[162:163], v[86:89], off offset:512
	global_store_dwordx4 v[162:163], v[82:85], off offset:528
	v_lshl_add_u64 v[162:163], v[162:163], 0, s[38:39]
	s_waitcnt vmcnt(21)
	v_cvt_f32_f16_e32 v236, v196
	v_cvt_f32_f16_sdwa v237, v196 dst_sel:DWORD dst_unused:UNUSED_PAD src0_sel:WORD_1
	v_cvt_f32_f16_e32 v238, v197
	v_cvt_f32_f16_sdwa v239, v197 dst_sel:DWORD dst_unused:UNUSED_PAD src0_sel:WORD_1
	v_cvt_f32_f16_e32 v240, v198
	v_cvt_f32_f16_sdwa v241, v198 dst_sel:DWORD dst_unused:UNUSED_PAD src0_sel:WORD_1
	v_cvt_f32_f16_e32 v242, v199
	v_cvt_f32_f16_sdwa v243, v199 dst_sel:DWORD dst_unused:UNUSED_PAD src0_sel:WORD_1
	v_pk_mul_f32 v[78:79], v[78:79], v[236:237]
	v_pk_mul_f32 v[80:81], v[80:81], v[238:239]
	v_pk_mul_f32 v[74:75], v[74:75], v[240:241]
	v_pk_mul_f32 v[76:77], v[76:77], v[242:243]
	global_store_dwordx4 v[162:163], v[78:81], off
	global_store_dwordx4 v[162:163], v[74:77], off offset:16
	s_waitcnt vmcnt(22)
	v_cvt_f32_f16_e32 v236, v200
	v_cvt_f32_f16_sdwa v237, v200 dst_sel:DWORD dst_unused:UNUSED_PAD src0_sel:WORD_1
	v_cvt_f32_f16_e32 v238, v201
	v_cvt_f32_f16_sdwa v239, v201 dst_sel:DWORD dst_unused:UNUSED_PAD src0_sel:WORD_1
	v_cvt_f32_f16_e32 v240, v202
	v_cvt_f32_f16_sdwa v241, v202 dst_sel:DWORD dst_unused:UNUSED_PAD src0_sel:WORD_1
	v_cvt_f32_f16_e32 v242, v203
	v_cvt_f32_f16_sdwa v243, v203 dst_sel:DWORD dst_unused:UNUSED_PAD src0_sel:WORD_1
	v_pk_mul_f32 v[70:71], v[70:71], v[236:237]
	v_pk_mul_f32 v[72:73], v[72:73], v[238:239]
	v_pk_mul_f32 v[66:67], v[66:67], v[240:241]
	v_pk_mul_f32 v[68:69], v[68:69], v[242:243]
	global_store_dwordx4 v[162:163], v[70:73], off offset:512
	global_store_dwordx4 v[162:163], v[66:69], off offset:528
	v_lshl_add_u64 v[162:163], s[38:39], 2, v[162:163]
	v_lshl_add_u64 v[162:163], v[162:163], 0, s[38:39]
	s_waitcnt vmcnt(23)
	v_cvt_f32_f16_e32 v236, v204
	v_cvt_f32_f16_sdwa v237, v204 dst_sel:DWORD dst_unused:UNUSED_PAD src0_sel:WORD_1
	v_cvt_f32_f16_e32 v238, v205
	v_cvt_f32_f16_sdwa v239, v205 dst_sel:DWORD dst_unused:UNUSED_PAD src0_sel:WORD_1
	v_cvt_f32_f16_e32 v240, v206
	v_cvt_f32_f16_sdwa v241, v206 dst_sel:DWORD dst_unused:UNUSED_PAD src0_sel:WORD_1
	v_cvt_f32_f16_e32 v242, v207
	v_cvt_f32_f16_sdwa v243, v207 dst_sel:DWORD dst_unused:UNUSED_PAD src0_sel:WORD_1
	v_pk_mul_f32 v[62:63], v[62:63], v[236:237]
	v_pk_mul_f32 v[64:65], v[64:65], v[238:239]
	v_pk_mul_f32 v[58:59], v[58:59], v[240:241]
	v_pk_mul_f32 v[60:61], v[60:61], v[242:243]
	global_store_dwordx4 v[162:163], v[62:65], off
	global_store_dwordx4 v[162:163], v[58:61], off offset:16
	s_waitcnt vmcnt(24)
	v_cvt_f32_f16_e32 v236, v208
	v_cvt_f32_f16_sdwa v237, v208 dst_sel:DWORD dst_unused:UNUSED_PAD src0_sel:WORD_1
	v_cvt_f32_f16_e32 v238, v209
	v_cvt_f32_f16_sdwa v239, v209 dst_sel:DWORD dst_unused:UNUSED_PAD src0_sel:WORD_1
	v_cvt_f32_f16_e32 v240, v210
	v_cvt_f32_f16_sdwa v241, v210 dst_sel:DWORD dst_unused:UNUSED_PAD src0_sel:WORD_1
	v_cvt_f32_f16_e32 v242, v211
	v_cvt_f32_f16_sdwa v243, v211 dst_sel:DWORD dst_unused:UNUSED_PAD src0_sel:WORD_1
	v_pk_mul_f32 v[54:55], v[54:55], v[236:237]
	v_pk_mul_f32 v[56:57], v[56:57], v[238:239]
	v_pk_mul_f32 v[50:51], v[50:51], v[240:241]
	v_pk_mul_f32 v[52:53], v[52:53], v[242:243]
	global_store_dwordx4 v[162:163], v[54:57], off offset:512
	global_store_dwordx4 v[162:163], v[50:53], off offset:528
	v_lshl_add_u64 v[162:163], v[162:163], 0, s[38:39]
	s_waitcnt vmcnt(25)
	v_cvt_f32_f16_e32 v236, v212
	v_cvt_f32_f16_sdwa v237, v212 dst_sel:DWORD dst_unused:UNUSED_PAD src0_sel:WORD_1
	v_cvt_f32_f16_e32 v238, v213
	v_cvt_f32_f16_sdwa v239, v213 dst_sel:DWORD dst_unused:UNUSED_PAD src0_sel:WORD_1
	v_cvt_f32_f16_e32 v240, v214
	v_cvt_f32_f16_sdwa v241, v214 dst_sel:DWORD dst_unused:UNUSED_PAD src0_sel:WORD_1
	v_cvt_f32_f16_e32 v242, v215
	v_cvt_f32_f16_sdwa v243, v215 dst_sel:DWORD dst_unused:UNUSED_PAD src0_sel:WORD_1
	v_pk_mul_f32 v[46:47], v[46:47], v[236:237]
	v_pk_mul_f32 v[48:49], v[48:49], v[238:239]
	v_pk_mul_f32 v[42:43], v[42:43], v[240:241]
	v_pk_mul_f32 v[44:45], v[44:45], v[242:243]
	global_store_dwordx4 v[162:163], v[46:49], off
	global_store_dwordx4 v[162:163], v[42:45], off offset:16
	s_waitcnt vmcnt(26)
	v_cvt_f32_f16_e32 v236, v216
	v_cvt_f32_f16_sdwa v237, v216 dst_sel:DWORD dst_unused:UNUSED_PAD src0_sel:WORD_1
	v_cvt_f32_f16_e32 v238, v217
	v_cvt_f32_f16_sdwa v239, v217 dst_sel:DWORD dst_unused:UNUSED_PAD src0_sel:WORD_1
	v_cvt_f32_f16_e32 v240, v218
	v_cvt_f32_f16_sdwa v241, v218 dst_sel:DWORD dst_unused:UNUSED_PAD src0_sel:WORD_1
	v_cvt_f32_f16_e32 v242, v219
	v_cvt_f32_f16_sdwa v243, v219 dst_sel:DWORD dst_unused:UNUSED_PAD src0_sel:WORD_1
	v_pk_mul_f32 v[38:39], v[38:39], v[236:237]
	v_pk_mul_f32 v[40:41], v[40:41], v[238:239]
	v_pk_mul_f32 v[34:35], v[34:35], v[240:241]
	v_pk_mul_f32 v[36:37], v[36:37], v[242:243]
	global_store_dwordx4 v[162:163], v[38:41], off offset:512
	global_store_dwordx4 v[162:163], v[34:37], off offset:528
	v_lshl_add_u64 v[162:163], v[162:163], 0, s[38:39]
	s_waitcnt vmcnt(27)
	v_cvt_f32_f16_e32 v236, v220
	v_cvt_f32_f16_sdwa v237, v220 dst_sel:DWORD dst_unused:UNUSED_PAD src0_sel:WORD_1
	v_cvt_f32_f16_e32 v238, v221
	v_cvt_f32_f16_sdwa v239, v221 dst_sel:DWORD dst_unused:UNUSED_PAD src0_sel:WORD_1
	v_cvt_f32_f16_e32 v240, v222
	v_cvt_f32_f16_sdwa v241, v222 dst_sel:DWORD dst_unused:UNUSED_PAD src0_sel:WORD_1
	v_cvt_f32_f16_e32 v242, v223
	v_cvt_f32_f16_sdwa v243, v223 dst_sel:DWORD dst_unused:UNUSED_PAD src0_sel:WORD_1
	v_pk_mul_f32 v[30:31], v[30:31], v[236:237]
	v_pk_mul_f32 v[32:33], v[32:33], v[238:239]
	v_pk_mul_f32 v[26:27], v[26:27], v[240:241]
	v_pk_mul_f32 v[28:29], v[28:29], v[242:243]
	global_store_dwordx4 v[162:163], v[30:33], off
	global_store_dwordx4 v[162:163], v[26:29], off offset:16
	s_waitcnt vmcnt(28)
	v_cvt_f32_f16_e32 v236, v224
	v_cvt_f32_f16_sdwa v237, v224 dst_sel:DWORD dst_unused:UNUSED_PAD src0_sel:WORD_1
	v_cvt_f32_f16_e32 v238, v225
	v_cvt_f32_f16_sdwa v239, v225 dst_sel:DWORD dst_unused:UNUSED_PAD src0_sel:WORD_1
	v_cvt_f32_f16_e32 v240, v226
	v_cvt_f32_f16_sdwa v241, v226 dst_sel:DWORD dst_unused:UNUSED_PAD src0_sel:WORD_1
	v_cvt_f32_f16_e32 v242, v227
	v_cvt_f32_f16_sdwa v243, v227 dst_sel:DWORD dst_unused:UNUSED_PAD src0_sel:WORD_1
	v_pk_mul_f32 v[22:23], v[22:23], v[236:237]
	v_pk_mul_f32 v[24:25], v[24:25], v[238:239]
	v_pk_mul_f32 v[18:19], v[18:19], v[240:241]
	v_pk_mul_f32 v[20:21], v[20:21], v[242:243]
	global_store_dwordx4 v[162:163], v[22:25], off offset:512
	global_store_dwordx4 v[162:163], v[18:21], off offset:528
	v_lshl_add_u64 v[162:163], v[162:163], 0, s[38:39]
	s_waitcnt vmcnt(29)
	v_cvt_f32_f16_e32 v236, v228
	v_cvt_f32_f16_sdwa v237, v228 dst_sel:DWORD dst_unused:UNUSED_PAD src0_sel:WORD_1
	v_cvt_f32_f16_e32 v238, v229
	v_cvt_f32_f16_sdwa v239, v229 dst_sel:DWORD dst_unused:UNUSED_PAD src0_sel:WORD_1
	v_cvt_f32_f16_e32 v240, v230
	v_cvt_f32_f16_sdwa v241, v230 dst_sel:DWORD dst_unused:UNUSED_PAD src0_sel:WORD_1
	v_cvt_f32_f16_e32 v242, v231
	v_cvt_f32_f16_sdwa v243, v231 dst_sel:DWORD dst_unused:UNUSED_PAD src0_sel:WORD_1
	v_pk_mul_f32 v[14:15], v[14:15], v[236:237]
	v_pk_mul_f32 v[16:17], v[16:17], v[238:239]
	v_pk_mul_f32 v[10:11], v[10:11], v[240:241]
	v_pk_mul_f32 v[12:13], v[12:13], v[242:243]
	global_store_dwordx4 v[162:163], v[14:17], off
	global_store_dwordx4 v[162:163], v[10:13], off offset:16
	s_waitcnt vmcnt(30)
	v_cvt_f32_f16_e32 v236, v232
	v_cvt_f32_f16_sdwa v237, v232 dst_sel:DWORD dst_unused:UNUSED_PAD src0_sel:WORD_1
	v_cvt_f32_f16_e32 v238, v233
	v_cvt_f32_f16_sdwa v239, v233 dst_sel:DWORD dst_unused:UNUSED_PAD src0_sel:WORD_1
	v_cvt_f32_f16_e32 v240, v234
	v_cvt_f32_f16_sdwa v241, v234 dst_sel:DWORD dst_unused:UNUSED_PAD src0_sel:WORD_1
	v_cvt_f32_f16_e32 v242, v235
	v_cvt_f32_f16_sdwa v243, v235 dst_sel:DWORD dst_unused:UNUSED_PAD src0_sel:WORD_1
	v_pk_mul_f32 v[6:7], v[6:7], v[236:237]
	v_pk_mul_f32 v[8:9], v[8:9], v[238:239]
	v_pk_mul_f32 v[2:3], v[2:3], v[240:241]
	v_pk_mul_f32 v[4:5], v[4:5], v[242:243]
	global_store_dwordx4 v[162:163], v[6:9], off offset:512
	global_store_dwordx4 v[162:163], v[2:5], off offset:528
	s_branch .Lepiof_done
.Lepiof_z1:
	s_waitcnt vmcnt(15)
	v_cvt_f32_f16_e32 v236, v168
	v_cvt_f32_f16_sdwa v237, v168 dst_sel:DWORD dst_unused:UNUSED_PAD src0_sel:WORD_1
	v_cvt_f32_f16_e32 v238, v169
	v_cvt_f32_f16_sdwa v239, v169 dst_sel:DWORD dst_unused:UNUSED_PAD src0_sel:WORD_1
	v_cvt_f32_f16_e32 v240, v170
	v_cvt_f32_f16_sdwa v241, v170 dst_sel:DWORD dst_unused:UNUSED_PAD src0_sel:WORD_1
	v_cvt_f32_f16_e32 v242, v171
	v_cvt_f32_f16_sdwa v243, v171 dst_sel:DWORD dst_unused:UNUSED_PAD src0_sel:WORD_1
	v_pk_mul_f32 v[126:127], v[126:127], v[236:237]
	v_pk_mul_f32 v[128:129], v[128:129], v[238:239]
	v_pk_mul_f32 v[122:123], v[122:123], v[240:241]
	v_pk_mul_f32 v[124:125], v[124:125], v[242:243]
	s_waitcnt vmcnt(14)
	v_cvt_f32_f16_e32 v236, v172
	v_cvt_f32_f16_sdwa v237, v172 dst_sel:DWORD dst_unused:UNUSED_PAD src0_sel:WORD_1
	v_cvt_f32_f16_e32 v238, v173
	v_cvt_f32_f16_sdwa v239, v173 dst_sel:DWORD dst_unused:UNUSED_PAD src0_sel:WORD_1
	v_cvt_f32_f16_e32 v240, v174
	v_cvt_f32_f16_sdwa v241, v174 dst_sel:DWORD dst_unused:UNUSED_PAD src0_sel:WORD_1
	v_cvt_f32_f16_e32 v242, v175
	v_cvt_f32_f16_sdwa v243, v175 dst_sel:DWORD dst_unused:UNUSED_PAD src0_sel:WORD_1
	v_pk_mul_f32 v[118:119], v[118:119], v[236:237]
	v_pk_mul_f32 v[120:121], v[120:121], v[238:239]
	v_pk_mul_f32 v[114:115], v[114:115], v[240:241]
	v_pk_mul_f32 v[116:117], v[116:117], v[242:243]
	s_waitcnt vmcnt(13)
	v_cvt_f32_f16_e32 v236, v176
	v_cvt_f32_f16_sdwa v237, v176 dst_sel:DWORD dst_unused:UNUSED_PAD src0_sel:WORD_1
	v_cvt_f32_f16_e32 v238, v177
	v_cvt_f32_f16_sdwa v239, v177 dst_sel:DWORD dst_unused:UNUSED_PAD src0_sel:WORD_1
	v_cvt_f32_f16_e32 v240, v178
	v_cvt_f32_f16_sdwa v241, v178 dst_sel:DWORD dst_unused:UNUSED_PAD src0_sel:WORD_1
	v_cvt_f32_f16_e32 v242, v179
	v_cvt_f32_f16_sdwa v243, v179 dst_sel:DWORD dst_unused:UNUSED_PAD src0_sel:WORD_1
	v_pk_mul_f32 v[110:111], v[110:111], v[236:237]
	v_pk_mul_f32 v[112:113], v[112:113], v[238:239]
	v_pk_mul_f32 v[106:107], v[106:107], v[240:241]
	v_pk_mul_f32 v[108:109], v[108:109], v[242:243]
	s_waitcnt vmcnt(12)
	v_cvt_f32_f16_e32 v236, v180
	v_cvt_f32_f16_sdwa v237, v180 dst_sel:DWORD dst_unused:UNUSED_PAD src0_sel:WORD_1
	v_cvt_f32_f16_e32 v238, v181
	v_cvt_f32_f16_sdwa v239, v181 dst_sel:DWORD dst_unused:UNUSED_PAD src0_sel:WORD_1
	v_cvt_f32_f16_e32 v240, v182
	v_cvt_f32_f16_sdwa v241, v182 dst_sel:DWORD dst_unused:UNUSED_PAD src0_sel:WORD_1
	v_cvt_f32_f16_e32 v242, v183
	v_cvt_f32_f16_sdwa v243, v183 dst_sel:DWORD dst_unused:UNUSED_PAD src0_sel:WORD_1
	v_pk_mul_f32 v[102:103], v[102:103], v[236:237]
	v_pk_mul_f32 v[104:105], v[104:105], v[238:239]
	v_pk_mul_f32 v[98:99], v[98:99], v[240:241]
	v_pk_mul_f32 v[100:101], v[100:101], v[242:243]
	s_waitcnt vmcnt(11)
	v_cvt_f32_f16_e32 v236, v184
	v_cvt_f32_f16_sdwa v237, v184 dst_sel:DWORD dst_unused:UNUSED_PAD src0_sel:WORD_1
	v_cvt_f32_f16_e32 v238, v185
	v_cvt_f32_f16_sdwa v239, v185 dst_sel:DWORD dst_unused:UNUSED_PAD src0_sel:WORD_1
	v_cvt_f32_f16_e32 v240, v186
	v_cvt_f32_f16_sdwa v241, v186 dst_sel:DWORD dst_unused:UNUSED_PAD src0_sel:WORD_1
	v_cvt_f32_f16_e32 v242, v187
	v_cvt_f32_f16_sdwa v243, v187 dst_sel:DWORD dst_unused:UNUSED_PAD src0_sel:WORD_1
	v_pk_mul_f32 v[94:95], v[94:95], v[236:237]
	v_pk_mul_f32 v[96:97], v[96:97], v[238:239]
	v_pk_mul_f32 v[90:91], v[90:91], v[240:241]
	v_pk_mul_f32 v[92:93], v[92:93], v[242:243]
	s_waitcnt vmcnt(10)
	v_cvt_f32_f16_e32 v236, v192
	v_cvt_f32_f16_sdwa v237, v192 dst_sel:DWORD dst_unused:UNUSED_PAD src0_sel:WORD_1
	v_cvt_f32_f16_e32 v238, v193
	v_cvt_f32_f16_sdwa v239, v193 dst_sel:DWORD dst_unused:UNUSED_PAD src0_sel:WORD_1
	v_cvt_f32_f16_e32 v240, v194
	v_cvt_f32_f16_sdwa v241, v194 dst_sel:DWORD dst_unused:UNUSED_PAD src0_sel:WORD_1
	v_cvt_f32_f16_e32 v242, v195
	v_cvt_f32_f16_sdwa v243, v195 dst_sel:DWORD dst_unused:UNUSED_PAD src0_sel:WORD_1
	v_pk_mul_f32 v[86:87], v[86:87], v[236:237]
	v_pk_mul_f32 v[88:89], v[88:89], v[238:239]
	v_pk_mul_f32 v[82:83], v[82:83], v[240:241]
	v_pk_mul_f32 v[84:85], v[84:85], v[242:243]
	s_waitcnt vmcnt(9)
	v_cvt_f32_f16_e32 v236, v196
	v_cvt_f32_f16_sdwa v237, v196 dst_sel:DWORD dst_unused:UNUSED_PAD src0_sel:WORD_1
	v_cvt_f32_f16_e32 v238, v197
	v_cvt_f32_f16_sdwa v239, v197 dst_sel:DWORD dst_unused:UNUSED_PAD src0_sel:WORD_1
	v_cvt_f32_f16_e32 v240, v198
	v_cvt_f32_f16_sdwa v241, v198 dst_sel:DWORD dst_unused:UNUSED_PAD src0_sel:WORD_1
	v_cvt_f32_f16_e32 v242, v199
	v_cvt_f32_f16_sdwa v243, v199 dst_sel:DWORD dst_unused:UNUSED_PAD src0_sel:WORD_1
	v_pk_mul_f32 v[78:79], v[78:79], v[236:237]
	v_pk_mul_f32 v[80:81], v[80:81], v[238:239]
	v_pk_mul_f32 v[74:75], v[74:75], v[240:241]
	v_pk_mul_f32 v[76:77], v[76:77], v[242:243]
	s_waitcnt vmcnt(8)
	v_cvt_f32_f16_e32 v236, v200
	v_cvt_f32_f16_sdwa v237, v200 dst_sel:DWORD dst_unused:UNUSED_PAD src0_sel:WORD_1
	v_cvt_f32_f16_e32 v238, v201
	v_cvt_f32_f16_sdwa v239, v201 dst_sel:DWORD dst_unused:UNUSED_PAD src0_sel:WORD_1
	v_cvt_f32_f16_e32 v240, v202
	v_cvt_f32_f16_sdwa v241, v202 dst_sel:DWORD dst_unused:UNUSED_PAD src0_sel:WORD_1
	v_cvt_f32_f16_e32 v242, v203
	v_cvt_f32_f16_sdwa v243, v203 dst_sel:DWORD dst_unused:UNUSED_PAD src0_sel:WORD_1
	v_pk_mul_f32 v[70:71], v[70:71], v[236:237]
	v_pk_mul_f32 v[72:73], v[72:73], v[238:239]
	v_pk_mul_f32 v[66:67], v[66:67], v[240:241]
	v_pk_mul_f32 v[68:69], v[68:69], v[242:243]
	s_waitcnt vmcnt(7)
	v_cvt_f32_f16_e32 v236, v204
	v_cvt_f32_f16_sdwa v237, v204 dst_sel:DWORD dst_unused:UNUSED_PAD src0_sel:WORD_1
	v_cvt_f32_f16_e32 v238, v205
	v_cvt_f32_f16_sdwa v239, v205 dst_sel:DWORD dst_unused:UNUSED_PAD src0_sel:WORD_1
	v_cvt_f32_f16_e32 v240, v206
	v_cvt_f32_f16_sdwa v241, v206 dst_sel:DWORD dst_unused:UNUSED_PAD src0_sel:WORD_1
	v_cvt_f32_f16_e32 v242, v207
	v_cvt_f32_f16_sdwa v243, v207 dst_sel:DWORD dst_unused:UNUSED_PAD src0_sel:WORD_1
	v_pk_mul_f32 v[62:63], v[62:63], v[236:237]
	v_pk_mul_f32 v[64:65], v[64:65], v[238:239]
	v_pk_mul_f32 v[58:59], v[58:59], v[240:241]
	v_pk_mul_f32 v[60:61], v[60:61], v[242:243]
	s_waitcnt vmcnt(6)
	v_cvt_f32_f16_e32 v236, v208
	v_cvt_f32_f16_sdwa v237, v208 dst_sel:DWORD dst_unused:UNUSED_PAD src0_sel:WORD_1
	v_cvt_f32_f16_e32 v238, v209
	v_cvt_f32_f16_sdwa v239, v209 dst_sel:DWORD dst_unused:UNUSED_PAD src0_sel:WORD_1
	v_cvt_f32_f16_e32 v240, v210
	v_cvt_f32_f16_sdwa v241, v210 dst_sel:DWORD dst_unused:UNUSED_PAD src0_sel:WORD_1
	v_cvt_f32_f16_e32 v242, v211
	v_cvt_f32_f16_sdwa v243, v211 dst_sel:DWORD dst_unused:UNUSED_PAD src0_sel:WORD_1
	v_pk_mul_f32 v[54:55], v[54:55], v[236:237]
	v_pk_mul_f32 v[56:57], v[56:57], v[238:239]
	v_pk_mul_f32 v[50:51], v[50:51], v[240:241]
	v_pk_mul_f32 v[52:53], v[52:53], v[242:243]
	s_waitcnt vmcnt(5)
	v_cvt_f32_f16_e32 v236, v212
	v_cvt_f32_f16_sdwa v237, v212 dst_sel:DWORD dst_unused:UNUSED_PAD src0_sel:WORD_1
	v_cvt_f32_f16_e32 v238, v213
	v_cvt_f32_f16_sdwa v239, v213 dst_sel:DWORD dst_unused:UNUSED_PAD src0_sel:WORD_1
	v_cvt_f32_f16_e32 v240, v214
	v_cvt_f32_f16_sdwa v241, v214 dst_sel:DWORD dst_unused:UNUSED_PAD src0_sel:WORD_1
	v_cvt_f32_f16_e32 v242, v215
	v_cvt_f32_f16_sdwa v243, v215 dst_sel:DWORD dst_unused:UNUSED_PAD src0_sel:WORD_1
	v_pk_mul_f32 v[46:47], v[46:47], v[236:237]
	v_pk_mul_f32 v[48:49], v[48:49], v[238:239]
	v_pk_mul_f32 v[42:43], v[42:43], v[240:241]
	v_pk_mul_f32 v[44:45], v[44:45], v[242:243]
	s_waitcnt vmcnt(4)
	v_cvt_f32_f16_e32 v236, v216
	v_cvt_f32_f16_sdwa v237, v216 dst_sel:DWORD dst_unused:UNUSED_PAD src0_sel:WORD_1
	v_cvt_f32_f16_e32 v238, v217
	v_cvt_f32_f16_sdwa v239, v217 dst_sel:DWORD dst_unused:UNUSED_PAD src0_sel:WORD_1
	v_cvt_f32_f16_e32 v240, v218
	v_cvt_f32_f16_sdwa v241, v218 dst_sel:DWORD dst_unused:UNUSED_PAD src0_sel:WORD_1
	v_cvt_f32_f16_e32 v242, v219
	v_cvt_f32_f16_sdwa v243, v219 dst_sel:DWORD dst_unused:UNUSED_PAD src0_sel:WORD_1
	v_pk_mul_f32 v[38:39], v[38:39], v[236:237]
	v_pk_mul_f32 v[40:41], v[40:41], v[238:239]
	v_pk_mul_f32 v[34:35], v[34:35], v[240:241]
	v_pk_mul_f32 v[36:37], v[36:37], v[242:243]
	s_waitcnt vmcnt(3)
	v_cvt_f32_f16_e32 v236, v220
	v_cvt_f32_f16_sdwa v237, v220 dst_sel:DWORD dst_unused:UNUSED_PAD src0_sel:WORD_1
	v_cvt_f32_f16_e32 v238, v221
	v_cvt_f32_f16_sdwa v239, v221 dst_sel:DWORD dst_unused:UNUSED_PAD src0_sel:WORD_1
	v_cvt_f32_f16_e32 v240, v222
	v_cvt_f32_f16_sdwa v241, v222 dst_sel:DWORD dst_unused:UNUSED_PAD src0_sel:WORD_1
	v_cvt_f32_f16_e32 v242, v223
	v_cvt_f32_f16_sdwa v243, v223 dst_sel:DWORD dst_unused:UNUSED_PAD src0_sel:WORD_1
	v_pk_mul_f32 v[30:31], v[30:31], v[236:237]
	v_pk_mul_f32 v[32:33], v[32:33], v[238:239]
	v_pk_mul_f32 v[26:27], v[26:27], v[240:241]
	v_pk_mul_f32 v[28:29], v[28:29], v[242:243]
	s_waitcnt vmcnt(2)
	v_cvt_f32_f16_e32 v236, v224
	v_cvt_f32_f16_sdwa v237, v224 dst_sel:DWORD dst_unused:UNUSED_PAD src0_sel:WORD_1
	v_cvt_f32_f16_e32 v238, v225
	v_cvt_f32_f16_sdwa v239, v225 dst_sel:DWORD dst_unused:UNUSED_PAD src0_sel:WORD_1
	v_cvt_f32_f16_e32 v240, v226
	v_cvt_f32_f16_sdwa v241, v226 dst_sel:DWORD dst_unused:UNUSED_PAD src0_sel:WORD_1
	v_cvt_f32_f16_e32 v242, v227
	v_cvt_f32_f16_sdwa v243, v227 dst_sel:DWORD dst_unused:UNUSED_PAD src0_sel:WORD_1
	v_pk_mul_f32 v[22:23], v[22:23], v[236:237]
	v_pk_mul_f32 v[24:25], v[24:25], v[238:239]
	v_pk_mul_f32 v[18:19], v[18:19], v[240:241]
	v_pk_mul_f32 v[20:21], v[20:21], v[242:243]
	s_waitcnt vmcnt(1)
	v_cvt_f32_f16_e32 v236, v228
	v_cvt_f32_f16_sdwa v237, v228 dst_sel:DWORD dst_unused:UNUSED_PAD src0_sel:WORD_1
	v_cvt_f32_f16_e32 v238, v229
	v_cvt_f32_f16_sdwa v239, v229 dst_sel:DWORD dst_unused:UNUSED_PAD src0_sel:WORD_1
	v_cvt_f32_f16_e32 v240, v230
	v_cvt_f32_f16_sdwa v241, v230 dst_sel:DWORD dst_unused:UNUSED_PAD src0_sel:WORD_1
	v_cvt_f32_f16_e32 v242, v231
	v_cvt_f32_f16_sdwa v243, v231 dst_sel:DWORD dst_unused:UNUSED_PAD src0_sel:WORD_1
	v_pk_mul_f32 v[14:15], v[14:15], v[236:237]
	v_pk_mul_f32 v[16:17], v[16:17], v[238:239]
	v_pk_mul_f32 v[10:11], v[10:11], v[240:241]
	v_pk_mul_f32 v[12:13], v[12:13], v[242:243]
	s_waitcnt vmcnt(0)
	v_cvt_f32_f16_e32 v236, v232
	v_cvt_f32_f16_sdwa v237, v232 dst_sel:DWORD dst_unused:UNUSED_PAD src0_sel:WORD_1
	v_cvt_f32_f16_e32 v238, v233
	v_cvt_f32_f16_sdwa v239, v233 dst_sel:DWORD dst_unused:UNUSED_PAD src0_sel:WORD_1
	v_cvt_f32_f16_e32 v240, v234
	v_cvt_f32_f16_sdwa v241, v234 dst_sel:DWORD dst_unused:UNUSED_PAD src0_sel:WORD_1
	v_cvt_f32_f16_e32 v242, v235
	v_cvt_f32_f16_sdwa v243, v235 dst_sel:DWORD dst_unused:UNUSED_PAD src0_sel:WORD_1
	v_pk_mul_f32 v[6:7], v[6:7], v[236:237]
	v_pk_mul_f32 v[8:9], v[8:9], v[238:239]
	v_pk_mul_f32 v[2:3], v[2:3], v[240:241]
	v_pk_mul_f32 v[4:5], v[4:5], v[242:243]
	global_load_dwordx4 v[168:171], v[162:163], off
	global_load_dwordx4 v[172:175], v[162:163], off offset:16
	global_load_dwordx4 v[176:179], v[162:163], off offset:512
	global_load_dwordx4 v[180:183], v[162:163], off offset:528
	v_lshl_add_u64 v[162:163], v[162:163], 0, s[38:39]
	global_load_dwordx4 v[192:195], v[162:163], off
	global_load_dwordx4 v[196:199], v[162:163], off offset:16
	global_load_dwordx4 v[200:203], v[162:163], off offset:512
	global_load_dwordx4 v[204:207], v[162:163], off offset:528
	v_lshl_add_u64 v[162:163], v[162:163], 0, s[38:39]
	global_load_dwordx4 v[208:211], v[162:163], off
	global_load_dwordx4 v[212:215], v[162:163], off offset:16
	global_load_dwordx4 v[216:219], v[162:163], off offset:512
	global_load_dwordx4 v[220:223], v[162:163], off offset:528
	v_lshl_add_u64 v[162:163], v[162:163], 0, s[38:39]
	global_load_dwordx4 v[224:227], v[162:163], off
	global_load_dwordx4 v[228:231], v[162:163], off offset:16
	global_load_dwordx4 v[232:235], v[162:163], off offset:512
	global_load_dwordx4 v[236:239], v[162:163], off offset:528
	v_lshl_add_u64 v[162:163], s[38:39], 2, v[162:163]
	v_lshl_add_u64 v[162:163], v[162:163], 0, s[38:39]
	s_waitcnt vmcnt(12)
	v_pk_add_f32 v[126:127], v[126:127], v[168:169]
	v_pk_add_f32 v[128:129], v[128:129], v[170:171]
	v_pk_add_f32 v[122:123], v[122:123], v[172:173]
	v_pk_add_f32 v[124:125], v[124:125], v[174:175]
	v_pk_add_f32 v[118:119], v[118:119], v[176:177]
	v_pk_add_f32 v[120:121], v[120:121], v[178:179]
	v_pk_add_f32 v[114:115], v[114:115], v[180:181]
	v_pk_add_f32 v[116:117], v[116:117], v[182:183]
	v_cvt_pk_bf16_f32 v126, v126, v127
	v_cvt_pk_bf16_f32 v127, v128, v129
	v_cvt_pk_bf16_f32 v128, v122, v123
	v_cvt_pk_bf16_f32 v129, v124, v125
	global_store_dwordx4 v[142:143], v[126:129], off
	v_cvt_pk_bf16_f32 v118, v118, v119
	v_cvt_pk_bf16_f32 v119, v120, v121
	v_cvt_pk_bf16_f32 v120, v114, v115
	v_cvt_pk_bf16_f32 v121, v116, v117
	global_store_dwordx4 v[142:143], v[118:121], off offset:256
	v_lshl_add_u64 v[142:143], v[142:143], 0, s[100:101]
	global_load_dwordx4 v[168:171], v[162:163], off
	global_load_dwordx4 v[172:175], v[162:163], off offset:16
	global_load_dwordx4 v[176:179], v[162:163], off offset:512
	global_load_dwordx4 v[180:183], v[162:163], off offset:528
	v_lshl_add_u64 v[162:163], v[162:163], 0, s[38:39]
	s_waitcnt vmcnt(14)
	v_pk_add_f32 v[110:111], v[110:111], v[192:193]
	v_pk_add_f32 v[112:113], v[112:113], v[194:195]
	v_pk_add_f32 v[106:107], v[106:107], v[196:197]
	v_pk_add_f32 v[108:109], v[108:109], v[198:199]
	v_pk_add_f32 v[102:103], v[102:103], v[200:201]
	v_pk_add_f32 v[104:105], v[104:105], v[202:203]
	v_pk_add_f32 v[98:99], v[98:99], v[204:205]
	v_pk_add_f32 v[100:101], v[100:101], v[206:207]
	v_cvt_pk_bf16_f32 v110, v110, v111
	v_cvt_pk_bf16_f32 v111, v112, v113
	v_cvt_pk_bf16_f32 v112, v106, v107
	v_cvt_pk_bf16_f32 v113, v108, v109
	global_store_dwordx4 v[142:143], v[110:113], off
	v_cvt_pk_bf16_f32 v102, v102, v103
	v_cvt_pk_bf16_f32 v103, v104, v105
	v_cvt_pk_bf16_f32 v104, v98, v99
	v_cvt_pk_bf16_f32 v105, v100, v101
	global_store_dwordx4 v[142:143], v[102:105], off offset:256
	v_lshl_add_u64 v[142:143], v[142:143], 0, s[100:101]
	global_load_dwordx4 v[192:195], v[162:163], off
	global_load_dwordx4 v[196:199], v[162:163], off offset:16
	global_load_dwordx4 v[200:203], v[162:163], off offset:512
	global_load_dwordx4 v[204:207], v[162:163], off offset:528
	v_lshl_add_u64 v[162:163], v[162:163], 0, s[38:39]
	s_waitcnt vmcnt(16)
	v_pk_add_f32 v[94:95], v[94:95], v[208:209]
	v_pk_add_f32 v[96:97], v[96:97], v[210:211]
	v_pk_add_f32 v[90:91], v[90:91], v[212:213]
	v_pk_add_f32 v[92:93], v[92:93], v[214:215]
	v_pk_add_f32 v[86:87], v[86:87], v[216:217]
	v_pk_add_f32 v[88:89], v[88:89], v[218:219]
	v_pk_add_f32 v[82:83], v[82:83], v[220:221]
	v_pk_add_f32 v[84:85], v[84:85], v[222:223]
	v_cvt_pk_bf16_f32 v94, v94, v95
	v_cvt_pk_bf16_f32 v95, v96, v97
	v_cvt_pk_bf16_f32 v96, v90, v91
	v_cvt_pk_bf16_f32 v97, v92, v93
	global_store_dwordx4 v[142:143], v[94:97], off
	v_cvt_pk_bf16_f32 v86, v86, v87
	v_cvt_pk_bf16_f32 v87, v88, v89
	v_cvt_pk_bf16_f32 v88, v82, v83
	v_cvt_pk_bf16_f32 v89, v84, v85
	global_store_dwordx4 v[142:143], v[86:89], off offset:256
	v_lshl_add_u64 v[142:143], v[142:143], 0, s[100:101]
	global_load_dwordx4 v[208:211], v[162:163], off
	global_load_dwordx4 v[212:215], v[162:163], off offset:16
	global_load_dwordx4 v[216:219], v[162:163], off offset:512
	global_load_dwordx4 v[220:223], v[162:163], off offset:528
	v_lshl_add_u64 v[162:163], v[162:163], 0, s[38:39]
	s_waitcnt vmcnt(18)
	v_pk_add_f32 v[78:79], v[78:79], v[224:225]
	v_pk_add_f32 v[80:81], v[80:81], v[226:227]
	v_pk_add_f32 v[74:75], v[74:75], v[228:229]
	v_pk_add_f32 v[76:77], v[76:77], v[230:231]
	v_pk_add_f32 v[70:71], v[70:71], v[232:233]
	v_pk_add_f32 v[72:73], v[72:73], v[234:235]
	v_pk_add_f32 v[66:67], v[66:67], v[236:237]
	v_pk_add_f32 v[68:69], v[68:69], v[238:239]
	v_cvt_pk_bf16_f32 v78, v78, v79
	v_cvt_pk_bf16_f32 v79, v80, v81
	v_cvt_pk_bf16_f32 v80, v74, v75
	v_cvt_pk_bf16_f32 v81, v76, v77
	global_store_dwordx4 v[142:143], v[78:81], off
	v_cvt_pk_bf16_f32 v70, v70, v71
	v_cvt_pk_bf16_f32 v71, v72, v73
	v_cvt_pk_bf16_f32 v72, v66, v67
	v_cvt_pk_bf16_f32 v73, v68, v69
	global_store_dwordx4 v[142:143], v[70:73], off offset:256
	v_lshl_add_u64 v[142:143], s[100:101], 2, v[142:143]
	v_lshl_add_u64 v[142:143], v[142:143], 0, s[100:101]
	global_load_dwordx4 v[224:227], v[162:163], off
	global_load_dwordx4 v[228:231], v[162:163], off offset:16
	global_load_dwordx4 v[232:235], v[162:163], off offset:512
	global_load_dwordx4 v[236:239], v[162:163], off offset:528
	s_waitcnt vmcnt(18)
	v_pk_add_f32 v[62:63], v[62:63], v[168:169]
	v_pk_add_f32 v[64:65], v[64:65], v[170:171]
	v_pk_add_f32 v[58:59], v[58:59], v[172:173]
	v_pk_add_f32 v[60:61], v[60:61], v[174:175]
	v_pk_add_f32 v[54:55], v[54:55], v[176:177]
	v_pk_add_f32 v[56:57], v[56:57], v[178:179]
	v_pk_add_f32 v[50:51], v[50:51], v[180:181]
	v_pk_add_f32 v[52:53], v[52:53], v[182:183]
	v_cvt_pk_bf16_f32 v62, v62, v63
	v_cvt_pk_bf16_f32 v63, v64, v65
	v_cvt_pk_bf16_f32 v64, v58, v59
	v_cvt_pk_bf16_f32 v65, v60, v61
	global_store_dwordx4 v[142:143], v[62:65], off
	v_cvt_pk_bf16_f32 v54, v54, v55
	v_cvt_pk_bf16_f32 v55, v56, v57
	v_cvt_pk_bf16_f32 v56, v50, v51
	v_cvt_pk_bf16_f32 v57, v52, v53
	global_store_dwordx4 v[142:143], v[54:57], off offset:256
	v_lshl_add_u64 v[142:143], v[142:143], 0, s[100:101]
	s_waitcnt vmcnt(14)
	v_pk_add_f32 v[46:47], v[46:47], v[192:193]
	v_pk_add_f32 v[48:49], v[48:49], v[194:195]
	v_pk_add_f32 v[42:43], v[42:43], v[196:197]
	v_pk_add_f32 v[44:45], v[44:45], v[198:199]
	v_pk_add_f32 v[38:39], v[38:39], v[200:201]
	v_pk_add_f32 v[40:41], v[40:41], v[202:203]
	v_pk_add_f32 v[34:35], v[34:35], v[204:205]
	v_pk_add_f32 v[36:37], v[36:37], v[206:207]
	v_cvt_pk_bf16_f32 v46, v46, v47
	v_cvt_pk_bf16_f32 v47, v48, v49
	v_cvt_pk_bf16_f32 v48, v42, v43
	v_cvt_pk_bf16_f32 v49, v44, v45
	global_store_dwordx4 v[142:143], v[46:49], off
	v_cvt_pk_bf16_f32 v38, v38, v39
	v_cvt_pk_bf16_f32 v39, v40, v41
	v_cvt_pk_bf16_f32 v40, v34, v35
	v_cvt_pk_bf16_f32 v41, v36, v37
	global_store_dwordx4 v[142:143], v[38:41], off offset:256
	v_lshl_add_u64 v[142:143], v[142:143], 0, s[100:101]
	s_waitcnt vmcnt(10)
	v_pk_add_f32 v[30:31], v[30:31], v[208:209]
	v_pk_add_f32 v[32:33], v[32:33], v[210:211]
	v_pk_add_f32 v[26:27], v[26:27], v[212:213]
	v_pk_add_f32 v[28:29], v[28:29], v[214:215]
	v_pk_add_f32 v[22:23], v[22:23], v[216:217]
	v_pk_add_f32 v[24:25], v[24:25], v[218:219]
	v_pk_add_f32 v[18:19], v[18:19], v[220:221]
	v_pk_add_f32 v[20:21], v[20:21], v[222:223]
	v_cvt_pk_bf16_f32 v30, v30, v31
	v_cvt_pk_bf16_f32 v31, v32, v33
	v_cvt_pk_bf16_f32 v32, v26, v27
	v_cvt_pk_bf16_f32 v33, v28, v29
	global_store_dwordx4 v[142:143], v[30:33], off
	v_cvt_pk_bf16_f32 v22, v22, v23
	v_cvt_pk_bf16_f32 v23, v24, v25
	v_cvt_pk_bf16_f32 v24, v18, v19
	v_cvt_pk_bf16_f32 v25, v20, v21
	global_store_dwordx4 v[142:143], v[22:25], off offset:256
	v_lshl_add_u64 v[142:143], v[142:143], 0, s[100:101]
	s_waitcnt vmcnt(6)
	v_pk_add_f32 v[14:15], v[14:15], v[224:225]
	v_pk_add_f32 v[16:17], v[16:17], v[226:227]
	v_pk_add_f32 v[10:11], v[10:11], v[228:229]
	v_pk_add_f32 v[12:13], v[12:13], v[230:231]
	v_pk_add_f32 v[6:7], v[6:7], v[232:233]
	v_pk_add_f32 v[8:9], v[8:9], v[234:235]
	v_pk_add_f32 v[2:3], v[2:3], v[236:237]
	v_pk_add_f32 v[4:5], v[4:5], v[238:239]
	v_cvt_pk_bf16_f32 v14, v14, v15
	v_cvt_pk_bf16_f32 v15, v16, v17
	v_cvt_pk_bf16_f32 v16, v10, v11
	v_cvt_pk_bf16_f32 v17, v12, v13
	global_store_dwordx4 v[142:143], v[14:17], off
	v_cvt_pk_bf16_f32 v6, v6, v7
	v_cvt_pk_bf16_f32 v7, v8, v9
	v_cvt_pk_bf16_f32 v8, v2, v3
	v_cvt_pk_bf16_f32 v9, v4, v5
	global_store_dwordx4 v[142:143], v[6:9], off offset:256
.Lepiof_done:
	s_andn2_b64 vcc, exec, s[36:37]
	s_mov_b64 s[2:3], -1
	s_cbranch_vccnz .LBB2_246
	s_branch .LBB2_322
.LBB2_322:
	s_andn2_b64 vcc, exec, s[4:5]
	s_cbranch_vccnz .LBB2_245
	s_barrier
	s_branch .LBB2_245
